# spatial gating: static s_setprio 1 for waves 4-7 during the phase (reset to 0 at phase exit)
# baseline (speedup 1.0000x reference)
; __device__ __forceinline__ float hsum4(f32x4 a) { return (a[0] + a[1]) + (a[2] + a[3]); }
; #define LAS __attribute__((address_space(3)))
; __device__ __forceinline__ int otid() { int t = threadIdx.x; asm volatile("" : "+v"(t)); return t; }
; __device__ __forceinline__ void sg_phase(const float* sgw, const float* sgb, const float* sgn, const bf16_t* U, const bf16_t* VTc, const float* ssv, bf16_t* GATED, LAS unsigned char* lds, int G) {
;     const int tid = otid(), lane = tid & 63, fr = lane & 15, fq = lane >> 4, wid = __builtin_amdgcn_readfirstlane(tid >> 6);
;     constexpr int WROW = 272, TAB_OFF = 36864;
;     LAS float* tab = (LAS float*)(lds + TAB_OFF);
;     for (int unit = blockIdx.x; unit < 2048; unit += G) {
;         const int chunk = unit >> 2, g = unit & 3, tok0 = chunk * 128;
;         bf16x8 bfr[2][4];
;         const bf16_t* vb = VTc + ((size_t)chunk * 1024 + g * 256 + 32 * wid + 8 * (fr >> 2) + (fr & 3)) * 128 + 8 * fq;
; #pragma unroll
;         for (int nf = 0; nf < 2; ++nf)
; #pragma unroll
;             for (int kk = 0; kk < 4; ++kk) bfr[nf][kk] = *(const bf16x8*)(vb + (size_t)nf * 4 * 128 + 32 * kk);
;         u32x4 uu[8];
;         const size_t rowoff = (size_t)(tok0 + fr) * 1024 + g * 256 + 32 * wid + 8 * fq;
; #pragma unroll
;         for (int tf = 0; tf < 8; ++tf) uu[tf] = *(const u32x4*)(U + rowoff + (size_t)tf * 16 * 1024);
;         if (tid < 128) { const f32x4* p = (const f32x4*)(ssv + (size_t)(tok0 + tid) * 8); tab[tid] = __builtin_amdgcn_rsqf((pg8::hsum4(p[0]) + pg8::hsum4(p[1])) * (1.0f / 1024.0f) + EPS); }
;         __syncthreads();
;         {
;             const int t = tid >> 2, sg0 = 32 * (tid & 3);
;             if (sg0 <= t) {
;                 const float* wrow = sgw + ((size_t)g * 128 + t) * 128 + sg0;
; #pragma unroll
;                 for (int c = 0; c < 4; ++c) { const f32x4 wa = *(const f32x4*)(wrow + 8 * c), wb = *(const f32x4*)(wrow + 8 * c + 4); float av[8];
; #pragma unroll
;                     for (int j = 0; j < 8; ++j) { const int s = sg0 + 8 * c + j; const float w = j < 4 ? wa[j] : wb[j - 4]; av[j] = (s <= t) ? w * tab[s] : 0.f; }
.LBB0_517:
	s_or_b64 exec, exec, s[4:5]
	s_waitcnt lgkmcnt(0)
	s_barrier
	s_load_dwordx2 s[6:7], s[58:59], 0x98
	s_waitcnt lgkmcnt(0)
	s_load_dwordx2 s[4:5], s[58:59], 0xa0
	s_waitcnt lgkmcnt(0)
	s_load_dwordx2 s[10:11], s[58:59], 0x90
	s_waitcnt lgkmcnt(0)
	s_waitcnt vmcnt(4)
	v_mov_b32_e32 v88, v228
	s_and_b64 vcc, exec, s[68:69]
	v_readfirstlane_b32 s2, v88
	s_cbranch_vccz .LBB0_587
	s_cmp_ge_u32 s2, 0x100
	s_cbranch_scc0 .Lprio_skip_sg
	s_setprio 1
.Lprio_skip_sg:
	v_readlane_b32 s12, v255, 0
	v_readlane_b32 s13, v255, 1
	s_add_u32 s4, s4, s12
	s_addc_u32 s5, s5, s13
	v_readlane_b32 s12, v255, 2
	v_readlane_b32 s13, v255, 3
	s_add_u32 s14, s10, s12
	s_addc_u32 s15, s11, s13
	v_readlane_b32 s10, v254, 60
	v_readlane_b32 s11, v254, 61
	s_add_u32 s10, s6, s10
	s_addc_u32 s11, s7, s11
	s_ashr_i32 s2, s2, 1
	v_lshlrev_b32_e32 v0, 1, v88
	s_and_b32 s12, s2, 0xffffffe0
	v_and_b32_e32 v0, 24, v0
	v_and_b32_e32 v1, 3, v88
	v_or3_b32 v74, v0, v1, s12
	v_lshrrev_b32_e32 v0, 1, v88
	v_and_b32_e32 v2, 24, v0
	v_lshlrev_b32_e32 v0, 5, v88
	v_lshlrev_b32_e32 v64, 1, v2
	v_and_b32_e32 v3, 0x60, v0
	v_lshl_add_u64 v[76:77], s[8:9], 0, v[64:65]
	v_or_b32_e32 v78, s12, v2
	v_ashrrev_i32_e32 v91, 2, v88
	v_add_u32_e32 v4, 0, v64
	v_lshlrev_b32_e32 v64, 2, v2
	v_or_b32_e32 v2, 8, v3
	v_cmp_le_i32_e64 s[24:25], v2, v91
	v_or_b32_e32 v2, 9, v3
	v_cmp_le_i32_e64 s[26:27], v2, v91
	v_or_b32_e32 v2, 10, v3
	v_cmp_le_i32_e64 s[28:29], v2, v91
	v_or_b32_e32 v2, 11, v3
	v_cmp_le_i32_e64 s[30:31], v2, v91
	v_or_b32_e32 v2, 12, v3
	v_cmp_le_i32_e64 s[34:35], v2, v91
	v_or_b32_e32 v2, 13, v3
	v_cmp_le_i32_e64 s[36:37], v2, v91
	v_or_b32_e32 v2, 14, v3
	v_cmp_le_i32_e64 s[38:39], v2, v91
	v_or_b32_e32 v2, 15, v3
	v_cmp_le_i32_e64 s[40:41], v2, v91
	v_or_b32_e32 v2, 16, v3
	v_cmp_le_i32_e64 s[42:43], v2, v91
	v_or_b32_e32 v2, 17, v3
	v_cmp_le_i32_e64 s[44:45], v2, v91
	v_or_b32_e32 v2, 18, v3
	v_cmp_le_i32_e64 s[46:47], v2, v91
	v_or_b32_e32 v2, 19, v3
	v_cmp_le_i32_e64 s[48:49], v2, v91
	v_or_b32_e32 v2, 20, v3
	v_cmp_le_i32_e64 s[50:51], v2, v91
	v_or_b32_e32 v2, 21, v3
	v_cmp_le_i32_e64 s[52:53], v2, v91
	v_or_b32_e32 v2, 22, v3
	v_cmp_le_i32_e64 s[54:55], v2, v91
	v_or_b32_e32 v2, 23, v3
	v_cmp_le_i32_e64 s[56:57], v2, v91
	v_or_b32_e32 v2, 24, v3
	s_ashr_i32 s13, s12, 31
	v_lshlrev_b32_e32 v0, 2, v3
	v_mov_b32_e32 v1, v65
	v_cmp_le_i32_e64 s[58:59], v2, v91
	v_or_b32_e32 v2, 25, v3
	v_lshl_add_u64 v[80:81], s[10:11], 0, v[0:1]
	s_lshl_b64 s[10:11], s[12:13], 2
	v_add_u32_e32 v92, 0, v0
	v_or_b32_e32 v0, 2, v3
	v_cmp_le_i32_e64 s[60:61], v2, v91
	v_or_b32_e32 v2, 26, v3
	v_mov_b32_e32 v75, s13
	v_mov_b32_e32 v79, s13
	s_add_u32 s10, s14, s10
	v_cmp_le_i32_e64 s[12:13], v0, v91
	v_or_b32_e32 v0, 3, v3
	v_cmp_le_i32_e64 s[62:63], v2, v91
	v_or_b32_e32 v2, 27, v3
	s_addc_u32 s11, s15, s11
	v_cmp_le_i32_e64 s[14:15], v0, v91
	v_or_b32_e32 v0, 4, v3
	v_cmp_le_i32_e64 s[64:65], v2, v91
	v_or_b32_e32 v2, 28, v3
	s_movk_i32 s2, 0x80
	v_cmp_le_i32_e64 s[16:17], v0, v91
	v_or_b32_e32 v0, 5, v3
	v_cmp_le_i32_e64 s[66:67], v2, v91
	v_or_b32_e32 v2, 29, v3
	v_cmp_gt_i32_e64 s[6:7], s2, v88
	s_movk_i32 s2, 0x110
	v_cmp_le_i32_e64 s[18:19], v0, v91
	v_or_b32_e32 v0, 6, v3
	v_cmp_le_i32_e64 s[68:69], v2, v91
	v_or_b32_e32 v2, 30, v3
	v_and_b32_e32 v89, 15, v88
	v_mul_lo_u32 v1, v91, s2
	v_lshl_add_u64 v[82:83], s[10:11], 0, v[64:65]
	v_cmp_lt_i32_e64 s[10:11], v3, v91
	v_cmp_le_i32_e64 s[20:21], v0, v91
	v_or_b32_e32 v0, 7, v3
	v_cmp_le_i32_e64 s[70:71], v2, v91
	v_or_b32_e32 v2, 31, v3
	v_add_u32_e32 v1, 0, v1
	v_writelane_b32 v255, s10, 9
	v_cmp_le_i32_e64 s[22:23], v0, v91
	v_lshlrev_b32_e32 v0, 1, v3
	v_cmp_le_i32_e64 s[72:73], v2, v91
	v_mul_u32_u24_e32 v2, 0x110, v89
	v_lshl_add_u32 v90, v88, 2, 0
	v_cmp_le_i32_e64 s[8:9], v3, v91
	v_writelane_b32 v255, s11, 10
	v_add_u32_e32 v93, v4, v2
	v_add_u32_e32 v94, v1, v0
	s_mov_b32 s2, s92
	s_mov_b32 s11, 0x10000
	s_branch .LBB0_521

; __device__ __forceinline__ void xcd_barrier(const XcdBarrier& b) {
;     asm volatile("s_waitcnt vmcnt(0)" ::: "memory");
;     __syncthreads();
;     if (threadIdx.x == 0) {
;         unsigned* bar = b.bar;
;         __builtin_amdgcn_s_waitcnt(0);
;         unsigned nloc = b.st[0], nx = b.st[1];
;         if (nloc == 0u) { xcd_barrier_complete(bar, b.x, nloc, nx); b.st[0] = nloc; b.st[1] = nx; }
.LBB0_587:
	s_setprio 0
	s_load_dwordx2 s[6:7], s[58:59], 0xb8
	s_waitcnt lgkmcnt(0)
	s_getreg_b32 s2, hwreg(HW_REG_XCC_ID, 0, 4)
	s_waitcnt vmcnt(0)
	s_barrier
	s_and_saveexec_b64 s[4:5], s[62:63]
	s_xor_b64 s[4:5], exec, s[4:5]
	s_cbranch_execz .LBB0_640
	v_readlane_b32 s8, v254, 31
	s_waitcnt vmcnt(0) expcnt(0) lgkmcnt(0)
	s_and_b32 s2, s2, 15
	v_mov_b32_e32 v0, s8
	ds_read_b32 v2, v0
	v_readlane_b32 s8, v254, 32
	s_waitcnt lgkmcnt(0)
	v_cmp_ne_u32_e32 vcc, 0, v2
	v_mov_b32_e32 v0, s8
	ds_read_b32 v0, v0
	s_cbranch_vccnz .LBB0_603
	s_add_u32 s8, s6, 0x9780200
	s_addc_u32 s9, s7, 0
	s_add_u32 s10, s6, 0x9780400
	s_addc_u32 s11, s7, 0
	s_add_u32 s12, s6, 0x9780500
	s_addc_u32 s13, s7, 0
	s_add_u32 s14, s6, 0x9780600
	s_addc_u32 s15, s7, 0
	s_add_u32 s16, s6, 0x9780700
	s_addc_u32 s17, s7, 0
	s_add_u32 s18, s6, 0x9780800
	s_addc_u32 s19, s7, 0
	s_add_u32 s20, s6, 0x9780900
	s_addc_u32 s21, s7, 0
	s_add_u32 s22, s6, 0x9780a00
	s_addc_u32 s23, s7, 0
	s_add_u32 s24, s6, 0x9780b00
	s_addc_u32 s25, s7, 0
	s_add_u32 s26, s6, 0x9780c00
	s_addc_u32 s27, s7, 0
	s_add_u32 s28, s6, 0x9780d00
	s_addc_u32 s29, s7, 0
	s_add_u32 s30, s6, 0x9780e00
	s_addc_u32 s31, s7, 0
	s_add_u32 s34, s6, 0x9780f00
	s_addc_u32 s35, s7, 0
	s_add_u32 s36, s6, 0x9781000
	s_addc_u32 s37, s7, 0
	s_add_u32 s38, s6, 0x9781100
	s_addc_u32 s39, s7, 0
	s_add_u32 s40, s6, 0x9781200
	s_addc_u32 s41, s7, 0
	s_add_u32 s42, s6, 0x9781300
	s_addc_u32 s43, s7, 0
	s_mov_b32 s50, 1
	s_branch .LBB0_591
